# both FFN-down K-loops: shared quarter-wise A-operand touch prefetch 4-5 K-tiles ahead (vmcnt 8->9 on three waits)
# baseline (speedup 1.0000x reference)
; #define PG8_STAGE(bufoff, gbase, voff) do { _Pragma("unroll") for (int _i = 0; _i < 2; ++_i) \
;         __builtin_amdgcn_global_load_lds((const unsigned*)((const char*)(gbase) + (voff)[_i]), (PG8_LAS unsigned*)(lds + (bufoff) + ldsw + _i * 8192), 16, 0, 0); } while (0)
; #define PG8_WAIT_V(n) asm volatile("s_waitcnt vmcnt(" #n ")" ::: "memory")
; #define PG8_BAR __builtin_amdgcn_s_barrier()
; template <class Epi, class Sched, bool ALIGN_EPI = false, bool SP2 = false>
; __device__ __forceinline__ void gemm_phase(PG8_LAS unsigned char* lds, const Gemm g, const Sched& S, const Epi& E) {
;     ...
;     for (int i = 0; i < 2; ++i) { int R, C; stage_rc(tid * 16 + i * 8192, R, C); const int Rb = Epi::PERM ? ((R & ~31) + perm32(R & 31)) : R;
;         voffA[i] = (unsigned)(R * K + C) * 2u; voffB[i] = (unsigned)(Rb * K + C) * 2u; }
;     const size_t kstep = (size_t)(BK * 2);
;     const size_t hstep = (size_t)HALF * K * 2;
;     const size_t tstep = 2 * hstep;
;     const unsigned ldsw = (unsigned)wid * 1024u;
;     const int aoff = lds_byte(wr * 64 + fr, fq * 8), boff = lds_byte(wc * 32 + fr, fq * 8);
;     ...
;         PG8_STAGE(PG8_SB(0, 0), cB, voffB); PG8_STAGE(PG8_SB(0, 1), cB + hstep, voffB); PG8_STAGE(PG8_SA(0, 0), cA, voffA); PG8_STAGE(PG8_SA(0, 1), cA + hstep, voffA);
;         if (wr == 1) PG8_BAR;
;         PG8_WAIT_V(2); PG8_BAR;
;         PG8_STAGE(PG8_SB(1, 0), cB + kstep, voffB); PG8_STAGE(PG8_SA(1, 0), cA + kstep, voffA); PG8_STAGE(PG8_SB(1, 1), cB + hstep + kstep, voffB);
;         PG8_WAIT_V(6); PG8_BAR;
.LBB0_960:
	s_mov_b64 s[12:13], 0x80
	s_and_b32 s3, s1, 3
	s_add_i32 m0, s48, 0x18000
	v_lshl_add_u64 v[6:7], v[6:7], 0, s[12:13]
	s_lshl_b32 s1, s0, 13
	s_lshl_b32 s14, s3, 12
	s_waitcnt vmcnt(2)
	s_barrier
	global_load_lds_dwordx4 v[6:7], off
	v_lshl_add_u64 v[2:3], v[2:3], 0, s[12:13]
	s_add_i32 m0, s48, 0x1a000
	s_add_i32 s53, s48, 0x8000
	s_add_i32 s60, s48, 0xa000
	global_load_lds_dwordx4 v[2:3], off
	v_lshl_add_u64 v[0:1], v[0:1], 0, s[12:13]
	s_mov_b32 m0, s53
	s_add_u32 s4, s44, 0xb0080
	global_load_lds_dwordx4 v[0:1], off
	v_lshl_add_u64 v[0:1], v[4:5], 0, s[12:13]
	s_mov_b32 m0, s60
	s_addc_u32 s5, s45, 0
	global_load_lds_dwordx4 v[0:1], off
	s_add_i32 m0, s48, 0x1c000
	v_lshl_add_u64 v[0:1], s[4:5], 0, v[130:131]
	global_load_lds_dwordx4 v[0:1], off
	v_lshl_add_u64 v[0:1], s[4:5], 0, v[134:135]
	s_add_i32 m0, s48, 0x1e000
	v_lshlrev_b32_e32 v5, 2, v230
	global_load_lds_dwordx4 v[0:1], off
	v_bfe_u32 v1, v230, 4, 2
	v_and_b32_e32 v0, 15, v230
	v_lshlrev_b32_e32 v3, 4, v1
	v_lshl_or_b32 v4, v0, 6, v3
	v_and_b32_e32 v5, 32, v5
	v_bitop3_b32 v4, v4, s1, v5 bitop3:0xde
	v_lshlrev_b32_e32 v6, 6, v230
	s_movk_i32 s1, 0x3c0
	v_and_or_b32 v6, v6, s1, v3
	s_cmpk_lt_u32 s2, 0x100
	v_lshl_or_b32 v150, s0, 6, v0
	v_lshlrev_b32_e32 v2, 3, v1
	v_bitop3_b32 v151, s14, v6, v5 bitop3:0xf6
	s_cselect_b64 s[14:15], -1, 0
	s_lshl_b32 s0, s0, 2
	v_lshl_or_b32 v152, s3, 5, v2
	s_or_b32 s2, s0, s3
	s_lshl_b32 s3, s3, 2
	s_lshl_b32 s0, s2, 6
	s_or_b32 s62, s3, 0x20200
	s_cmp_eq_u32 s2, 0
	s_cselect_b64 s[18:19], -1, 0
	s_ashr_i32 s63, s11, 31
	s_ashr_i32 s64, s10, 31
	s_add_u32 s20, s58, 0x1e000000
	v_or3_b32 v153, s0, v3, v0
	s_addc_u32 s21, s59, 0
	v_add_u16_e32 v0, v8, v9
	s_waitcnt vmcnt(6)
	s_add_u32 s58, s58, 0x10000
	v_lshrrev_b16_e32 v0, 1, v0
	s_addc_u32 s59, s59, 0
	v_add_lshl_u32 v136, v10, v0, 1
	v_add_lshl_u32 v138, v11, v0, 1
	s_add_i32 s66, 0, 0x10000
	s_add_i32 s67, 0, 0x14000
	v_mbcnt_lo_u32_b32 v0, -1, 0
	s_movk_i32 s61, 0x100
	v_cmp_eq_u32_e64 s[0:1], 0, v1
	s_mov_b64 s[22:23], 0x10000
	v_mov_b32_e32 v137, v131
	v_mov_b32_e32 v139, v131
	v_mov_b64_e32 v[140:141], 0x300
	v_mov_b64_e32 v[142:143], 0x2ff
	s_movk_i32 s65, 0x61
	v_add_u32_e32 v154, s66, v151
	v_add_u32_e32 v155, s67, v151
	v_add_u32_e32 v156, 0, v4
	v_mbcnt_hi_u32_b32 v157, -1, v0
	s_mov_b64 s[24:25], 0x20000
	s_mov_b64 s[26:27], 0x30000
	s_mov_b64 s[30:31], 0x80000
	s_mov_b64 s[34:35], 0x90000
	s_mov_b64 s[36:37], 0xa0000
	v_mov_b32_e32 v158, 0x358637bd
	s_mov_b32 s68, 0xf800000
	v_mov_b32_e32 v159, 0x260
	v_mov_b32_e32 v160, 0x20200
	v_mov_b32_e32 v161, 0x21200
	s_barrier
	v_bfe_u32 v232, v230, 6, 2
	v_bfe_u32 v231, v230, 2, 4
	v_lshl_add_u32 v231, v232, 4, v231
	v_mul_u32_u24_e32 v231, 0x1600, v231
	v_lshrrev_b32_e32 v232, 8, v230
	v_lshl_add_u32 v231, v232, 7, v231
	v_and_b32_e32 v232, 1, v230
	v_lshl_add_u32 v231, v232, 6, v231
	s_branch .LBB0_963

; #define PG8_STAGE(bufoff, gbase, voff) do { _Pragma("unroll") for (int _i = 0; _i < 2; ++_i) \
;         __builtin_amdgcn_global_load_lds((const unsigned*)((const char*)(gbase) + (voff)[_i]), (PG8_LAS unsigned*)(lds + (bufoff) + ldsw + _i * 8192), 16, 0, 0); } while (0)
; #define PG8_LDA(dst, b, h) do { _Pragma("unroll") for (int m = 0; m < 4; ++m) _Pragma("unroll") for (int k = 0; k < 2; ++k) dst[m][k] = *(const PG8_LAS bf16x8*)(lds + PG8_SA(b, h) + aoff + m * 2048 + k * 1024); } while (0)
; #define PG8_LDB(dst, b, h) do { _Pragma("unroll") for (int n = 0; n < 2; ++n) _Pragma("unroll") for (int k = 0; k < 2; ++k) dst[n][k] = *(const PG8_LAS bf16x8*)(lds + PG8_SB(b, h) + boff + n * 2048 + k * 1024); } while (0)
; #define PG8_MMA(ai, bj, At, Bt) do { __builtin_amdgcn_s_setprio(1); _Pragma("unroll") for (int m = 0; m < 4; ++m) _Pragma("unroll") for (int n = 0; n < 2; ++n) _Pragma("unroll") for (int k = 0; k < 2; ++k) \
;         acc[ai][bj][m][n] = __builtin_amdgcn_mfma_f32_16x16x32_bf16(Bt[n][k], At[m][k], acc[ai][bj][m][n], 0, 0, 0); __builtin_amdgcn_s_setprio(0); } while (0)
; #define PG8_WAIT_V(n) asm volatile("s_waitcnt vmcnt(" #n ")" ::: "memory")
; #define PG8_WAIT_L(n) asm volatile("s_waitcnt lgkmcnt(" #n ")" ::: "memory")
; #define PG8_BAR __builtin_amdgcn_s_barrier()
; #define PG8_SCHED __builtin_amdgcn_sched_barrier(0)
; template <class Epi, class Sched, bool ALIGN_EPI = false, bool SP2 = false>
; __device__ __forceinline__ void gemm_phase(PG8_LAS unsigned char* lds, const Gemm g, const Sched& S, const Epi& E) {
;     ...
;             PG8_LDB(B0, 0, 0); PG8_LDB(B1, 0, 1); PG8_SCHED; PG8_LDA(At, 0, 0); PG8_STAGE(PG8_SA(1, 1), a1 + hstep, voffA);
;             PG8_WAIT_V(8); PG8_WAIT_L(0); PG8_BAR; PG8_MMA(0, 0, At, B0); PG8_MMA(0, 1, At, B1); PG8_BAR; PG8_SCHED;
;             PG8_LDA(At, 0, 1); PG8_STAGE(PG8_SB(0, 0), b2, voffB); PG8_STAGE(PG8_SB(0, 1), b2 + hstep, voffB); PG8_STAGE(PG8_SA(0, 0), a2, voffA);
.LBB0_970:
	ds_read_b128 v[144:147], v154
	ds_read_b128 v[162:165], v154 offset:1024
	ds_read_b128 v[166:169], v154 offset:2048
	ds_read_b128 v[170:173], v154 offset:3072
	ds_read_b128 v[174:177], v155
	ds_read_b128 v[178:181], v155 offset:1024
	ds_read_b128 v[182:185], v155 offset:2048
	ds_read_b128 v[186:189], v155 offset:3072
	s_add_u32 s44, s4, 0xfff50080
	s_addc_u32 s45, s5, -1
	s_cmp_eq_u32 s73, 40
	s_cselect_b32 s47, s39, s45
	s_cselect_b32 s46, s38, s44
	s_cselect_b32 s45, s41, s72
	s_cselect_b32 s44, s40, s43
	v_lshl_add_u64 v[148:149], s[4:5], 0, v[136:137]
	s_add_i32 m0, s48, 0xc000
	ds_read_b128 v[190:193], v156
	ds_read_b128 v[194:197], v156 offset:1024
	ds_read_b128 v[198:201], v156 offset:2048
	ds_read_b128 v[202:205], v156 offset:3072
	ds_read_b128 v[206:209], v156 offset:4096
	ds_read_b128 v[210:213], v156 offset:5120
	ds_read_b128 v[214:217], v156 offset:6144
	ds_read_b128 v[218:221], v156 offset:7168
	global_load_lds_dwordx4 v[148:149], off
	v_lshl_add_u64 v[148:149], s[4:5], 0, v[138:139]
	s_add_i32 m0, s48, 0xe000
	s_nop 0
	global_load_lds_dwordx4 v[148:149], off
	s_add_u32 s100, s4, 0xfff50180
	s_addc_u32 s101, s5, -1
	s_mul_i32 s98, s42, 0x58000
	v_add_u32_e32 v232, s98, v231
	global_load_dword v233, v232, s[100:101]
	s_waitcnt vmcnt(9)
	s_waitcnt lgkmcnt(0)
	s_barrier
	s_setprio 1
	s_waitcnt lgkmcnt(0)
	v_mfma_f32_16x16x32_bf16 v[124:127], v[144:147], v[190:193], v[124:127]
	v_mfma_f32_16x16x32_bf16 v[120:123], v[166:169], v[190:193], v[120:123]
	v_mfma_f32_16x16x32_bf16 v[104:107], v[144:147], v[198:201], v[104:107]
	v_mfma_f32_16x16x32_bf16 v[108:111], v[166:169], v[198:201], v[108:111]
	v_mfma_f32_16x16x32_bf16 v[88:91], v[144:147], v[206:209], v[88:91]
	v_mfma_f32_16x16x32_bf16 v[92:95], v[166:169], v[206:209], v[92:95]
	v_mfma_f32_16x16x32_bf16 v[72:75], v[144:147], v[214:217], v[72:75]
	v_mfma_f32_16x16x32_bf16 v[76:79], v[166:169], v[214:217], v[76:79]
	v_mfma_f32_16x16x32_bf16 v[124:127], v[162:165], v[194:197], v[124:127]
	v_mfma_f32_16x16x32_bf16 v[120:123], v[170:173], v[194:197], v[120:123]
	v_mfma_f32_16x16x32_bf16 v[104:107], v[162:165], v[202:205], v[104:107]
	v_mfma_f32_16x16x32_bf16 v[108:111], v[170:173], v[202:205], v[108:111]
	v_mfma_f32_16x16x32_bf16 v[88:91], v[162:165], v[210:213], v[88:91]
	v_mfma_f32_16x16x32_bf16 v[92:95], v[170:173], v[210:213], v[92:95]
	v_mfma_f32_16x16x32_bf16 v[72:75], v[162:165], v[218:221], v[72:75]
	v_mfma_f32_16x16x32_bf16 v[76:79], v[170:173], v[218:221], v[76:79]
	s_setprio 0
	s_setprio 1
	v_mfma_f32_16x16x32_bf16 v[116:119], v[174:177], v[190:193], v[116:119]
	v_mfma_f32_16x16x32_bf16 v[112:115], v[182:185], v[190:193], v[112:115]
	v_mfma_f32_16x16x32_bf16 v[100:103], v[174:177], v[198:201], v[100:103]
	v_mfma_f32_16x16x32_bf16 v[96:99], v[182:185], v[198:201], v[96:99]
	v_mfma_f32_16x16x32_bf16 v[84:87], v[174:177], v[206:209], v[84:87]
	v_mfma_f32_16x16x32_bf16 v[80:83], v[182:185], v[206:209], v[80:83]
	v_mfma_f32_16x16x32_bf16 v[68:71], v[174:177], v[214:217], v[68:71]
	v_mfma_f32_16x16x32_bf16 v[64:67], v[182:185], v[214:217], v[64:67]
	v_mfma_f32_16x16x32_bf16 v[116:119], v[178:181], v[194:197], v[116:119]
	v_mfma_f32_16x16x32_bf16 v[112:115], v[186:189], v[194:197], v[112:115]
	v_mfma_f32_16x16x32_bf16 v[100:103], v[178:181], v[202:205], v[100:103]
	v_mfma_f32_16x16x32_bf16 v[96:99], v[186:189], v[202:205], v[96:99]
	v_mfma_f32_16x16x32_bf16 v[84:87], v[178:181], v[210:213], v[84:87]
	v_mfma_f32_16x16x32_bf16 v[80:83], v[186:189], v[210:213], v[80:83]
	v_mfma_f32_16x16x32_bf16 v[68:71], v[178:181], v[218:221], v[68:71]
	v_mfma_f32_16x16x32_bf16 v[64:67], v[186:189], v[218:221], v[64:67]
	s_setprio 0
	s_barrier
	s_add_i32 s74, s66, s33
	v_lshl_add_u64 v[148:149], s[44:45], 0, v[130:131]
	s_mov_b32 m0, s74
	ds_read_b128 v[190:193], v156 offset:16384
	ds_read_b128 v[194:197], v156 offset:17408
	ds_read_b128 v[198:201], v156 offset:18432
	ds_read_b128 v[202:205], v156 offset:19456
	ds_read_b128 v[206:209], v156 offset:20480
	ds_read_b128 v[210:213], v156 offset:21504
	ds_read_b128 v[214:217], v156 offset:22528
	ds_read_b128 v[218:221], v156 offset:23552
	global_load_lds_dwordx4 v[148:149], off
	s_add_i32 m0, s74, 0x2000
	s_add_u32 s74, s44, 0xb0000
	v_lshl_add_u64 v[222:223], s[44:45], 0, v[134:135]
	s_addc_u32 s75, s45, 0
	s_add_i32 s76, s67, s33
	global_load_lds_dwordx4 v[222:223], off
	v_lshl_add_u64 v[224:225], s[74:75], 0, v[130:131]
	s_mov_b32 m0, s76
	v_lshl_add_u64 v[226:227], s[46:47], 0, v[132:133]
	global_load_lds_dwordx4 v[224:225], off
	v_lshl_add_u64 v[224:225], s[74:75], 0, v[134:135]
	s_add_i32 m0, s76, 0x2000
	s_nop 0
	global_load_lds_dwordx4 v[224:225], off
	v_lshl_add_u64 v[224:225], s[46:47], 0, v[128:129]
	s_mov_b32 m0, s48
	s_nop 0
	global_load_lds_dwordx4 v[224:225], off
	s_mov_b32 m0, s49
	s_nop 0
	global_load_lds_dwordx4 v[226:227], off
	s_waitcnt vmcnt(9)
	s_waitcnt lgkmcnt(0)
	s_barrier
; #define PG8_STAGE(bufoff, gbase, voff) do { _Pragma("unroll") for (int _i = 0; _i < 2; ++_i) \
;         __builtin_amdgcn_global_load_lds((const unsigned*)((const char*)(gbase) + (voff)[_i]), (PG8_LAS unsigned*)(lds + (bufoff) + ldsw + _i * 8192), 16, 0, 0); } while (0)
; #define PG8_LDA(dst, b, h) do { _Pragma("unroll") for (int m = 0; m < 4; ++m) _Pragma("unroll") for (int k = 0; k < 2; ++k) dst[m][k] = *(const PG8_LAS bf16x8*)(lds + PG8_SA(b, h) + aoff + m * 2048 + k * 1024); } while (0)
; #define PG8_LDB(dst, b, h) do { _Pragma("unroll") for (int n = 0; n < 2; ++n) _Pragma("unroll") for (int k = 0; k < 2; ++k) dst[n][k] = *(const PG8_LAS bf16x8*)(lds + PG8_SB(b, h) + boff + n * 2048 + k * 1024); } while (0)
; #define PG8_MMA(ai, bj, At, Bt) do { __builtin_amdgcn_s_setprio(1); _Pragma("unroll") for (int m = 0; m < 4; ++m) _Pragma("unroll") for (int n = 0; n < 2; ++n) _Pragma("unroll") for (int k = 0; k < 2; ++k) \
;         acc[ai][bj][m][n] = __builtin_amdgcn_mfma_f32_16x16x32_bf16(Bt[n][k], At[m][k], acc[ai][bj][m][n], 0, 0, 0); __builtin_amdgcn_s_setprio(0); } while (0)
; #define PG8_WAIT_V(n) asm volatile("s_waitcnt vmcnt(" #n ")" ::: "memory")
; #define PG8_WAIT_L(n) asm volatile("s_waitcnt lgkmcnt(" #n ")" ::: "memory")
; #define PG8_BAR __builtin_amdgcn_s_barrier()
; #define PG8_SCHED __builtin_amdgcn_sched_barrier(0)
; template <class Epi, class Sched, bool ALIGN_EPI = false, bool SP2 = false>
; __device__ __forceinline__ void gemm_phase(PG8_LAS unsigned char* lds, const Gemm g, const Sched& S, const Epi& E) {
;     ...
;             PG8_WAIT_V(8); PG8_WAIT_L(0); PG8_BAR; PG8_MMA(1, 0, At, B0); PG8_MMA(1, 1, At, B1); PG8_BAR; PG8_SCHED;
;             PG8_LDB(B0, 1, 0); PG8_LDB(B1, 1, 1); PG8_SCHED; PG8_LDA(At, 1, 0); PG8_STAGE(PG8_SA(0, 1), a2 + hstep, voffA);
;             PG8_WAIT_V(8); PG8_WAIT_L(0); PG8_BAR; PG8_MMA(0, 0, At, B0); PG8_MMA(0, 1, At, B1); PG8_BAR; PG8_SCHED;
	s_setprio 1
	s_waitcnt lgkmcnt(0)
	v_mfma_f32_16x16x32_bf16 v[56:59], v[144:147], v[190:193], v[56:59]
	v_mfma_f32_16x16x32_bf16 v[60:63], v[166:169], v[190:193], v[60:63]
	v_mfma_f32_16x16x32_bf16 v[40:43], v[144:147], v[198:201], v[40:43]
	v_mfma_f32_16x16x32_bf16 v[44:47], v[166:169], v[198:201], v[44:47]
	v_mfma_f32_16x16x32_bf16 v[24:27], v[144:147], v[206:209], v[24:27]
	v_mfma_f32_16x16x32_bf16 v[28:31], v[166:169], v[206:209], v[28:31]
	v_mfma_f32_16x16x32_bf16 v[8:11], v[144:147], v[214:217], v[8:11]
	v_mfma_f32_16x16x32_bf16 v[12:15], v[166:169], v[214:217], v[12:15]
	v_mfma_f32_16x16x32_bf16 v[56:59], v[162:165], v[194:197], v[56:59]
	v_mfma_f32_16x16x32_bf16 v[60:63], v[170:173], v[194:197], v[60:63]
	v_mfma_f32_16x16x32_bf16 v[40:43], v[162:165], v[202:205], v[40:43]
	v_mfma_f32_16x16x32_bf16 v[44:47], v[170:173], v[202:205], v[44:47]
	v_mfma_f32_16x16x32_bf16 v[24:27], v[162:165], v[210:213], v[24:27]
	v_mfma_f32_16x16x32_bf16 v[28:31], v[170:173], v[210:213], v[28:31]
	v_mfma_f32_16x16x32_bf16 v[8:11], v[162:165], v[218:221], v[8:11]
	v_mfma_f32_16x16x32_bf16 v[12:15], v[170:173], v[218:221], v[12:15]
	s_setprio 0
	s_setprio 1
	v_mfma_f32_16x16x32_bf16 v[52:55], v[174:177], v[190:193], v[52:55]
	v_mfma_f32_16x16x32_bf16 v[48:51], v[182:185], v[190:193], v[48:51]
	v_mfma_f32_16x16x32_bf16 v[36:39], v[174:177], v[198:201], v[36:39]
	v_mfma_f32_16x16x32_bf16 v[32:35], v[182:185], v[198:201], v[32:35]
	v_mfma_f32_16x16x32_bf16 v[20:23], v[174:177], v[206:209], v[20:23]
	v_mfma_f32_16x16x32_bf16 v[16:19], v[182:185], v[206:209], v[16:19]
	v_mfma_f32_16x16x32_bf16 v[4:7], v[174:177], v[214:217], v[4:7]
	v_mfma_f32_16x16x32_bf16 v[0:3], v[182:185], v[214:217], v[0:3]
	v_mfma_f32_16x16x32_bf16 v[52:55], v[178:181], v[194:197], v[52:55]
	v_mfma_f32_16x16x32_bf16 v[48:51], v[186:189], v[194:197], v[48:51]
	v_mfma_f32_16x16x32_bf16 v[36:39], v[178:181], v[202:205], v[36:39]
	v_mfma_f32_16x16x32_bf16 v[32:35], v[186:189], v[202:205], v[32:35]
	v_mfma_f32_16x16x32_bf16 v[20:23], v[178:181], v[210:213], v[20:23]
	v_mfma_f32_16x16x32_bf16 v[16:19], v[186:189], v[210:213], v[16:19]
	v_mfma_f32_16x16x32_bf16 v[4:7], v[178:181], v[218:221], v[4:7]
	v_mfma_f32_16x16x32_bf16 v[0:3], v[186:189], v[218:221], v[0:3]
	s_setprio 0
	s_barrier
	s_add_i32 s74, 0, 0x18000
	s_add_i32 s75, 0, 0x1c000
	v_add_u32_e32 v170, s74, v151
	v_add_u32_e32 v186, s75, v151
	ds_read_b128 v[144:147], v170
	ds_read_b128 v[162:165], v170 offset:1024
	ds_read_b128 v[166:169], v170 offset:2048
	ds_read_b128 v[170:173], v170 offset:3072
	ds_read_b128 v[174:177], v186
	ds_read_b128 v[178:181], v186 offset:1024
	ds_read_b128 v[182:185], v186 offset:2048
	ds_read_b128 v[186:189], v186 offset:3072
	s_add_u32 s46, s46, 0xb0000
	s_addc_u32 s47, s47, 0
	s_mov_b32 m0, s50
	v_lshl_add_u64 v[228:229], s[46:47], 0, v[128:129]
	ds_read_b128 v[190:193], v156 offset:32768
	ds_read_b128 v[194:197], v156 offset:33792
	ds_read_b128 v[198:201], v156 offset:34816
	ds_read_b128 v[202:205], v156 offset:35840
	ds_read_b128 v[206:209], v156 offset:36864
	ds_read_b128 v[210:213], v156 offset:37888
	ds_read_b128 v[214:217], v156 offset:38912
	ds_read_b128 v[218:221], v156 offset:39936
	global_load_lds_dwordx4 v[228:229], off
	v_lshl_add_u64 v[228:229], s[46:47], 0, v[132:133]
	s_mov_b32 m0, s51
	s_nop 0
	global_load_lds_dwordx4 v[228:229], off
	s_waitcnt vmcnt(9)
	s_waitcnt lgkmcnt(0)
	s_barrier
	s_setprio 1
	s_waitcnt lgkmcnt(0)
	v_mfma_f32_16x16x32_bf16 v[124:127], v[144:147], v[190:193], v[124:127]
	v_mfma_f32_16x16x32_bf16 v[120:123], v[166:169], v[190:193], v[120:123]
	v_mfma_f32_16x16x32_bf16 v[104:107], v[144:147], v[198:201], v[104:107]
	v_mfma_f32_16x16x32_bf16 v[108:111], v[166:169], v[198:201], v[108:111]
	v_mfma_f32_16x16x32_bf16 v[88:91], v[144:147], v[206:209], v[88:91]
	v_mfma_f32_16x16x32_bf16 v[92:95], v[166:169], v[206:209], v[92:95]
	v_mfma_f32_16x16x32_bf16 v[72:75], v[144:147], v[214:217], v[72:75]
	v_mfma_f32_16x16x32_bf16 v[76:79], v[166:169], v[214:217], v[76:79]
	v_mfma_f32_16x16x32_bf16 v[124:127], v[162:165], v[194:197], v[124:127]
	v_mfma_f32_16x16x32_bf16 v[120:123], v[170:173], v[194:197], v[120:123]
	v_mfma_f32_16x16x32_bf16 v[104:107], v[162:165], v[202:205], v[104:107]
	v_mfma_f32_16x16x32_bf16 v[108:111], v[170:173], v[202:205], v[108:111]
	v_mfma_f32_16x16x32_bf16 v[88:91], v[162:165], v[210:213], v[88:91]
	v_mfma_f32_16x16x32_bf16 v[92:95], v[170:173], v[210:213], v[92:95]
	v_mfma_f32_16x16x32_bf16 v[72:75], v[162:165], v[218:221], v[72:75]
	v_mfma_f32_16x16x32_bf16 v[76:79], v[170:173], v[218:221], v[76:79]
	s_setprio 0
	s_setprio 1
	v_mfma_f32_16x16x32_bf16 v[116:119], v[174:177], v[190:193], v[116:119]
	v_mfma_f32_16x16x32_bf16 v[112:115], v[182:185], v[190:193], v[112:115]
	v_mfma_f32_16x16x32_bf16 v[100:103], v[174:177], v[198:201], v[100:103]
	v_mfma_f32_16x16x32_bf16 v[96:99], v[182:185], v[198:201], v[96:99]
	v_mfma_f32_16x16x32_bf16 v[84:87], v[174:177], v[206:209], v[84:87]
	v_mfma_f32_16x16x32_bf16 v[80:83], v[182:185], v[206:209], v[80:83]
	v_mfma_f32_16x16x32_bf16 v[68:71], v[174:177], v[214:217], v[68:71]
	v_mfma_f32_16x16x32_bf16 v[64:67], v[182:185], v[214:217], v[64:67]
	v_mfma_f32_16x16x32_bf16 v[116:119], v[178:181], v[194:197], v[116:119]
	v_mfma_f32_16x16x32_bf16 v[112:115], v[186:189], v[194:197], v[112:115]
	v_mfma_f32_16x16x32_bf16 v[100:103], v[178:181], v[202:205], v[100:103]
	v_mfma_f32_16x16x32_bf16 v[96:99], v[186:189], v[202:205], v[96:99]
	v_mfma_f32_16x16x32_bf16 v[84:87], v[178:181], v[210:213], v[84:87]
	v_mfma_f32_16x16x32_bf16 v[80:83], v[186:189], v[210:213], v[80:83]
	v_mfma_f32_16x16x32_bf16 v[68:71], v[178:181], v[218:221], v[68:71]
	v_mfma_f32_16x16x32_bf16 v[64:67], v[186:189], v[218:221], v[64:67]
	s_setprio 0
	s_barrier
; #define PG8_STAGE(bufoff, gbase, voff) do { _Pragma("unroll") for (int _i = 0; _i < 2; ++_i) \
;         __builtin_amdgcn_global_load_lds((const unsigned*)((const char*)(gbase) + (voff)[_i]), (PG8_LAS unsigned*)(lds + (bufoff) + ldsw + _i * 8192), 16, 0, 0); } while (0)
; #define PG8_LDA(dst, b, h) do { _Pragma("unroll") for (int m = 0; m < 4; ++m) _Pragma("unroll") for (int k = 0; k < 2; ++k) dst[m][k] = *(const PG8_LAS bf16x8*)(lds + PG8_SA(b, h) + aoff + m * 2048 + k * 1024); } while (0)
; #define PG8_MMA(ai, bj, At, Bt) do { __builtin_amdgcn_s_setprio(1); _Pragma("unroll") for (int m = 0; m < 4; ++m) _Pragma("unroll") for (int n = 0; n < 2; ++n) _Pragma("unroll") for (int k = 0; k < 2; ++k) \
;         acc[ai][bj][m][n] = __builtin_amdgcn_mfma_f32_16x16x32_bf16(Bt[n][k], At[m][k], acc[ai][bj][m][n], 0, 0, 0); __builtin_amdgcn_s_setprio(0); } while (0)
; #define PG8_WAIT_V(n) asm volatile("s_waitcnt vmcnt(" #n ")" ::: "memory")
; #define PG8_WAIT_L(n) asm volatile("s_waitcnt lgkmcnt(" #n ")" ::: "memory")
; #define PG8_BAR __builtin_amdgcn_s_barrier()
; #define PG8_SCHED __builtin_amdgcn_sched_barrier(0)
; template <class Epi, class Sched, bool ALIGN_EPI = false, bool SP2 = false>
; __device__ __forceinline__ void gemm_phase(PG8_LAS unsigned char* lds, const Gemm g, const Sched& S, const Epi& E) {
;     ...
;             PG8_LDA(At, 1, 1); PG8_STAGE(PG8_SB(1, 0), b3, voffB); PG8_STAGE(PG8_SB(1, 1), b3 + hstep, voffB); PG8_STAGE(PG8_SA(1, 0), a3, voffA);
;             PG8_WAIT_V(8); PG8_WAIT_L(0); PG8_BAR; PG8_MMA(1, 0, At, B0); PG8_MMA(1, 1, At, B1); PG8_BAR; PG8_SCHED;
;     ...
;         if constexpr (ALIGN_EPI) { if (wr == 0) PG8_BAR; }
	s_add_i32 s46, s74, s33
	v_lshl_add_u64 v[148:149], v[148:149], 0, s[12:13]
	s_mov_b32 m0, s46
	ds_read_b128 v[190:193], v156 offset:49152
	ds_read_b128 v[194:197], v156 offset:50176
	ds_read_b128 v[198:201], v156 offset:51200
	ds_read_b128 v[202:205], v156 offset:52224
	ds_read_b128 v[206:209], v156 offset:53248
	ds_read_b128 v[210:213], v156 offset:54272
	ds_read_b128 v[214:217], v156 offset:55296
	ds_read_b128 v[218:221], v156 offset:56320
	global_load_lds_dwordx4 v[148:149], off
	s_add_i32 m0, s46, 0x2000
	s_add_u32 s44, s44, 0xb0080
	v_lshl_add_u64 v[148:149], v[222:223], 0, s[12:13]
	s_addc_u32 s45, s45, 0
	s_add_i32 s46, s75, s33
	global_load_lds_dwordx4 v[148:149], off
	v_lshl_add_u64 v[148:149], s[44:45], 0, v[130:131]
	s_mov_b32 m0, s46
	s_nop 0
	global_load_lds_dwordx4 v[148:149], off
	v_lshl_add_u64 v[148:149], s[44:45], 0, v[134:135]
	s_add_i32 m0, s46, 0x2000
	s_nop 0
	global_load_lds_dwordx4 v[148:149], off
	v_lshl_add_u64 v[148:149], v[224:225], 0, s[12:13]
	s_mov_b32 m0, s53
	s_nop 0
	global_load_lds_dwordx4 v[148:149], off
	v_lshl_add_u64 v[148:149], v[226:227], 0, s[12:13]
	s_mov_b32 m0, s60
	s_nop 0
	global_load_lds_dwordx4 v[148:149], off
	s_waitcnt vmcnt(8)
	s_waitcnt lgkmcnt(0)
	s_barrier
	s_setprio 1
	s_waitcnt lgkmcnt(0)
	v_mfma_f32_16x16x32_bf16 v[56:59], v[144:147], v[190:193], v[56:59]
	v_mfma_f32_16x16x32_bf16 v[60:63], v[166:169], v[190:193], v[60:63]
	v_mfma_f32_16x16x32_bf16 v[40:43], v[144:147], v[198:201], v[40:43]
	v_mfma_f32_16x16x32_bf16 v[44:47], v[166:169], v[198:201], v[44:47]
	v_mfma_f32_16x16x32_bf16 v[24:27], v[144:147], v[206:209], v[24:27]
	v_mfma_f32_16x16x32_bf16 v[28:31], v[166:169], v[206:209], v[28:31]
	v_mfma_f32_16x16x32_bf16 v[8:11], v[144:147], v[214:217], v[8:11]
	v_mfma_f32_16x16x32_bf16 v[12:15], v[166:169], v[214:217], v[12:15]
	v_mfma_f32_16x16x32_bf16 v[56:59], v[162:165], v[194:197], v[56:59]
	v_mfma_f32_16x16x32_bf16 v[60:63], v[170:173], v[194:197], v[60:63]
	v_mfma_f32_16x16x32_bf16 v[40:43], v[162:165], v[202:205], v[40:43]
	v_mfma_f32_16x16x32_bf16 v[44:47], v[170:173], v[202:205], v[44:47]
	v_mfma_f32_16x16x32_bf16 v[24:27], v[162:165], v[210:213], v[24:27]
	v_mfma_f32_16x16x32_bf16 v[28:31], v[170:173], v[210:213], v[28:31]
	v_mfma_f32_16x16x32_bf16 v[8:11], v[162:165], v[218:221], v[8:11]
	v_mfma_f32_16x16x32_bf16 v[12:15], v[170:173], v[218:221], v[12:15]
	s_setprio 0
	s_setprio 1
	v_mfma_f32_16x16x32_bf16 v[52:55], v[174:177], v[190:193], v[52:55]
	v_mfma_f32_16x16x32_bf16 v[48:51], v[182:185], v[190:193], v[48:51]
	v_mfma_f32_16x16x32_bf16 v[36:39], v[174:177], v[198:201], v[36:39]
	v_mfma_f32_16x16x32_bf16 v[32:35], v[182:185], v[198:201], v[32:35]
	v_mfma_f32_16x16x32_bf16 v[20:23], v[174:177], v[206:209], v[20:23]
	v_mfma_f32_16x16x32_bf16 v[16:19], v[182:185], v[206:209], v[16:19]
	v_mfma_f32_16x16x32_bf16 v[4:7], v[174:177], v[214:217], v[4:7]
	v_mfma_f32_16x16x32_bf16 v[0:3], v[182:185], v[214:217], v[0:3]
	v_mfma_f32_16x16x32_bf16 v[52:55], v[178:181], v[194:197], v[52:55]
	v_mfma_f32_16x16x32_bf16 v[48:51], v[186:189], v[194:197], v[48:51]
	v_mfma_f32_16x16x32_bf16 v[36:39], v[178:181], v[202:205], v[36:39]
	v_mfma_f32_16x16x32_bf16 v[32:35], v[186:189], v[202:205], v[32:35]
	v_mfma_f32_16x16x32_bf16 v[20:23], v[178:181], v[210:213], v[20:23]
	v_mfma_f32_16x16x32_bf16 v[16:19], v[186:189], v[210:213], v[16:19]
	v_mfma_f32_16x16x32_bf16 v[4:7], v[178:181], v[218:221], v[4:7]
	v_mfma_f32_16x16x32_bf16 v[0:3], v[186:189], v[218:221], v[0:3]
	s_setprio 0
	s_barrier
	s_add_i32 s73, s73, 2
	s_add_u32 s4, s4, 0x100
	s_addc_u32 s5, s5, 0
	s_add_u32 s43, s43, 0x100
	s_addc_u32 s72, s72, 0
	s_cmp_gt_u32 s73, 41
	s_cbranch_scc0 .LBB0_970
	s_and_b64 vcc, exec, s[14:15]
	s_cbranch_vccz .LBB0_973
	s_barrier
